# v194 stack plus 64-bit register clears in P3 and the device-wide barrier sites' L1 invalidate on wave 1
# baseline (speedup 1.0000x reference)
.Lgi616_w1:
	s_mov_b64 s[6:7], exec
	v_readlane_b32 s0, v254, 8
	v_readlane_b32 s1, v254, 9
	s_and_b64 s[0:1], s[6:7], s[0:1]
	s_mov_b64 exec, s[0:1]
	s_cbranch_execz .LBB0_616
	v_readlane_b32 s0, v255, 42
	s_cmp_eq_u32 s0, 1
	s_cbranch_scc0 .Lb4_go
	s_cmp_lt_u32 s74, 32
	s_cbranch_scc1 .Lb4_scan
	s_and_b32 s0, s74, 7
	s_lshl_b32 s0, s0, 6
	s_add_u32 s0, s0, 0x5200
	s_add_u32 s2, s92, s0
	s_addc_u32 s3, s93, 0
	v_mov_b32_e32 v0, 1
	s_waitcnt vmcnt(0) lgkmcnt(0)
	global_atomic_add v1, v197, v0, s[2:3] sc0
	s_waitcnt vmcnt(0)
	v_readfirstlane_b32 s0, v1
	v_readlane_b32 s1, v255, 31
	s_add_u32 s1, s1, 1
	s_mul_i32 s1, s1, 28
	s_sub_u32 s1, s1, 1
	s_cmp_eq_u32 s0, s1
	s_cbranch_scc0 .Lb4_go
	buffer_wbl2 sc1
	s_waitcnt vmcnt(0)
	global_atomic_add v197, v0, s[2:3] offset:512
	s_waitcnt vmcnt(0)
	s_branch .Lb4_go
